# down-GEMM residual epilogue (ph8/ph15): all 16 base-row loads issued up front into free registers, counted waits
# speedup vs baseline: 1.0030x; 1.0030x over previous
;     __device__ __forceinline__ void ld(Ld& L, size_t o) const {
; #pragma unroll
;         for (int bj = 0; bj < 2; ++bj) { if (BASEF32) { L.a[bj][0] = *(const f32x4*)((const float*)base + o + bj * HALF); L.a[bj][1] = *(const f32x4*)((const float*)base + o + bj * HALF + 4); }
;             else { const v4u w = *(const v4u*)((const bf16*)base + o + bj * HALF); L.a[bj][0] = __builtin_bit_cast(f32x4, w); } }
;     }
;     __device__ __forceinline__ void operator()(const pg8::f32x4 (&acc)[2][2][4][2], const Unit& u, int wr, int wc, int fr, int fq) const {
;         const int row0 = u.pm * BM + wr * 64 + fr, col0 = u.pn * BM + wc * 32 + 8 * fq;
;         Ld nx; ld(nx, (size_t)row0 * DM_ + col0);
; #pragma unroll
;         for (int k = 0; k < 8; ++k) { const int ai = k >> 2, m = k & 3; const int row = row0 + ai * HALF + m * 16; float q = 0.f; const Ld cu = nx;
;             if (k < 7) ld(nx, (size_t)(row0 + ((k + 1) >> 2) * HALF + ((k + 1) & 3) * 16) * DM_ + col0);
.LBB0_779:
	v_lshl_add_u32 v156, s52, 8, v1
	v_lshl_or_b32 v154, s51, 8, v163
	v_ashrrev_i32_e32 v157, 31, v156
	v_ashrrev_i32_e32 v155, 31, v154
	v_lshlrev_b64 v[130:131], 11, v[156:157]
	v_lshl_add_u64 v[130:131], s[16:17], 0, v[130:131]
	v_lshlrev_b64 v[132:133], 1, v[154:155]
	v_lshl_add_u64 v[178:179], v[130:131], 0, v[132:133]
	global_load_dwordx4 v[170:173], v[178:179], off
	global_load_dwordx4 v[174:177], v[178:179], off offset:256
	v_or_b32_e32 v158, 16, v156
	v_ashrrev_i32_e32 v159, 31, v158
	v_lshlrev_b64 v[130:131], 11, v[158:159]
	v_lshl_add_u64 v[130:131], s[16:17], 0, v[130:131]
	v_lshl_add_u64 v[160:161], v[130:131], 0, v[132:133]
	global_load_dwordx4 v[134:137], v[160:161], off
	global_load_dwordx4 v[130:133], v[160:161], off offset:256
	v_lshlrev_b32_e32 v250, 11, v156
	v_lshl_add_u32 v250, v154, 1, v250
	s_add_u32 s98, s16, 0x10000
	s_addc_u32 s99, s17, 0
	global_load_dwordx4 v[188:191], v250, s[98:99]
	global_load_dwordx4 v[192:195], v250, s[98:99] offset:256
	s_add_u32 s98, s16, 0x18000
	s_addc_u32 s99, s17, 0
	global_load_dwordx4 v[196:199], v250, s[98:99]
	global_load_dwordx4 v[200:203], v250, s[98:99] offset:256
	s_add_u32 s98, s16, 0x40000
	s_addc_u32 s99, s17, 0
	global_load_dwordx4 v[204:207], v250, s[98:99]
	global_load_dwordx4 v[208:211], v250, s[98:99] offset:256
	s_add_u32 s98, s16, 0x48000
	s_addc_u32 s99, s17, 0
	global_load_dwordx4 v[212:215], v250, s[98:99]
	global_load_dwordx4 v[230:233], v250, s[98:99] offset:256
	s_add_u32 s98, s16, 0x50000
	s_addc_u32 s99, s17, 0
	global_load_dwordx4 v[234:237], v250, s[98:99]
	global_load_dwordx4 v[238:241], v250, s[98:99] offset:256
	s_add_u32 s98, s16, 0x58000
	s_addc_u32 s99, s17, 0
	global_load_dwordx4 v[242:245], v250, s[98:99]
	global_load_dwordx4 v[246:249], v250, s[98:99] offset:256
	v_and_b32_e32 v169, 64, v167
	v_xor_b32_e32 v168, 16, v167
	v_add_u32_e32 v169, 64, v169
	v_xor_b32_e32 v180, 32, v167
	v_cmp_lt_i32_e32 vcc, v168, v169
	s_lshl_b32 s26, s51, 2
	s_ashr_i32 s27, s26, 31
	v_cndmask_b32_e32 v168, v167, v168, vcc
	v_cmp_lt_i32_e32 vcc, v180, v169
	v_lshlrev_b32_e32 v168, 2, v168
	s_waitcnt vmcnt(12)
	v_and_b32_e32 v181, 0xffff0000, v170
	v_cndmask_b32_e32 v169, v167, v180, vcc
	v_lshlrev_b32_e32 v180, 16, v170
	v_lshlrev_b32_e32 v170, 16, v171
	v_and_b32_e32 v171, 0xffff0000, v171
	v_lshlrev_b32_e32 v184, 16, v174
	v_and_b32_e32 v185, 0xffff0000, v174
	v_lshlrev_b32_e32 v174, 16, v175
	v_and_b32_e32 v175, 0xffff0000, v175
	v_lshlrev_b32_e32 v182, 16, v172
	v_and_b32_e32 v183, 0xffff0000, v172
	v_lshlrev_b32_e32 v172, 16, v173
	v_and_b32_e32 v173, 0xffff0000, v173
	v_lshlrev_b32_e32 v186, 16, v176
	v_and_b32_e32 v187, 0xffff0000, v176
	v_lshlrev_b32_e32 v176, 16, v177
	v_and_b32_e32 v177, 0xffff0000, v177
	v_pk_add_f32 v[128:129], v[128:129], v[170:171]
	v_pk_add_f32 v[126:127], v[126:127], v[180:181]
	v_pk_add_f32 v[120:121], v[120:121], v[174:175]
	v_pk_add_f32 v[118:119], v[118:119], v[184:185]
	v_pk_add_f32 v[124:125], v[124:125], v[172:173]
	v_pk_add_f32 v[122:123], v[122:123], v[182:183]
	v_pk_add_f32 v[170:171], v[116:117], v[176:177]
	v_pk_add_f32 v[172:173], v[114:115], v[186:187]
	v_mul_f32_e32 v116, v127, v127
	v_mul_f32_e32 v117, v129, v129
	v_cvt_pk_bf16_f32 v114, v126, v127
	v_cvt_pk_bf16_f32 v115, v128, v129
	v_mul_f32_e32 v127, v119, v119
	v_mul_f32_e32 v129, v121, v121
	v_mul_f32_e32 v174, v123, v123
	v_mul_f32_e32 v176, v173, v173
	v_fmac_f32_e32 v116, v126, v126
	v_fmac_f32_e32 v117, v128, v128
	v_fmac_f32_e32 v127, v118, v118
	v_fmac_f32_e32 v129, v120, v120
	v_mul_f32_e32 v175, v125, v125
	v_mul_f32_e32 v177, v171, v171
	v_fmac_f32_e32 v174, v122, v122
	v_fmac_f32_e32 v176, v172, v172
	v_add_f32_e32 v116, v116, v117
	v_add_f32_e32 v117, v127, v129
	v_fmac_f32_e32 v175, v124, v124
	v_fmac_f32_e32 v177, v170, v170
	v_add_f32_e32 v116, v174, v116
	v_add_f32_e32 v117, v176, v117
	v_add_f32_e32 v116, v175, v116
	v_add_f32_e32 v117, v177, v117
	v_add_f32_e32 v126, v116, v117
	ds_bpermute_b32 v127, v168, v126
	v_cvt_pk_bf16_f32 v116, v122, v123
	v_cvt_pk_bf16_f32 v117, v124, v125
	global_store_dwordx4 v[178:179], v[114:117], off
	s_waitcnt lgkmcnt(0)
	s_nop 0
	v_add_f32_e32 v114, v126, v127
	v_lshlrev_b32_e32 v126, 2, v169
	ds_bpermute_b32 v115, v126, v114
	v_cvt_pk_bf16_f32 v116, v118, v119
	v_cvt_pk_bf16_f32 v117, v120, v121
	v_cvt_pk_bf16_f32 v118, v172, v173
	v_cvt_pk_bf16_f32 v119, v170, v171
	global_store_dwordx4 v[178:179], v[116:119], off offset:256
	s_and_saveexec_b64 s[28:29], s[8:9]
	s_cbranch_execz .LBB0_781
	v_lshlrev_b64 v[116:117], 6, v[156:157]
	v_lshl_add_u64 v[116:117], s[18:19], 0, v[116:117]
	v_lshl_add_u64 v[116:117], s[26:27], 2, v[116:117]
	s_lshl_b32 s4, s40, 2
	v_lshl_add_u64 v[116:117], v[116:117], 0, s[4:5]
	s_waitcnt lgkmcnt(0)
	v_add_f32_e32 v114, v114, v115
	global_store_dword v[116:117], v114, off
; __device__ __forceinline__ unsigned cvt_pk_bf16(float lo, float hi) { unsigned r; asm volatile("v_cvt_pk_bf16_f32 %0, %1, %2" : "=v"(r) : "v"(lo), "v"(hi)); return r; }
; __device__ __forceinline__ float bflo(unsigned w) { return __uint_as_float(w << 16); }
; __device__ __forceinline__ float bfhi(unsigned w) { return __uint_as_float(w & 0xffff0000u); }
;     __device__ __forceinline__ void operator()(const pg8::f32x4 (&acc)[2][2][4][2], const Unit& u, int wr, int wc, int fr, int fq) const {
;     ...
;         for (int k = 0; k < 8; ++k) { const int ai = k >> 2, m = k & 3; const int row = row0 + ai * HALF + m * 16; float q = 0.f; const Ld cu = nx;
;             if (k < 7) ld(nx, (size_t)(row0 + ((k + 1) >> 2) * HALF + ((k + 1) & 3) * 16) * DM_ + col0);
; #pragma unroll
;             for (int bj = 0; bj < 2; ++bj) { const size_t o = (size_t)row * DM_ + col0 + bj * HALF; f32x4 b0, b1;
;                 if (BASEF32) { b0 = cu.a[bj][0]; b1 = cu.a[bj][1]; }
;                 else { const v4u w = __builtin_bit_cast(v4u, cu.a[bj][0]); b0 = (f32x4){bflo(w.x), bfhi(w.x), bflo(w.y), bfhi(w.y)}; b1 = (f32x4){bflo(w.z), bfhi(w.z), bflo(w.w), bfhi(w.w)}; }
;                 const f32x4 r0 = b0 + acc[ai][bj][m][0], r1 = b1 + acc[ai][bj][m][1];
;                 q += (r0[0] * r0[0] + r0[1] * r0[1]) + (r0[2] * r0[2] + r0[3] * r0[3]) + (r1[0] * r1[0] + r1[1] * r1[1]) + (r1[2] * r1[2] + r1[3] * r1[3]);
;                 v4u w; w.x = cvt_pk_bf16(r0[0], r0[1]); w.y = cvt_pk_bf16(r0[2], r0[3]); w.z = cvt_pk_bf16(r1[0], r1[1]); w.w = cvt_pk_bf16(r1[2], r1[3]); *(v4u*)(out + o) = w; }
;             q += __shfl_xor(q, 16); q += __shfl_xor(q, 32); if (fq == 0) ssq[(size_t)row * 16 + u.pn * 4 + wc] = q; }
.LBB0_781:
	s_or_b64 exec, exec, s[28:29]
	v_or_b32_e32 v122, 32, v156
	v_ashrrev_i32_e32 v123, 31, v122
	s_waitcnt lgkmcnt(0)
	v_lshlrev_b64 v[114:115], 11, v[122:123]
	v_lshl_add_u64 v[114:115], s[16:17], 0, v[114:115]
	v_lshl_add_u64 v[124:125], v[154:155], 1, v[114:115]
	v_lshlrev_b32_e32 v128, 16, v134
	v_and_b32_e32 v129, 0xffff0000, v134
	v_lshlrev_b32_e32 v134, 16, v135
	v_and_b32_e32 v135, 0xffff0000, v135
	v_lshlrev_b32_e32 v170, 16, v136
	v_and_b32_e32 v171, 0xffff0000, v136
	v_lshlrev_b32_e32 v136, 16, v137
	v_and_b32_e32 v137, 0xffff0000, v137
	v_pk_add_f32 v[112:113], v[112:113], v[134:135]
	v_pk_add_f32 v[110:111], v[110:111], v[128:129]
	v_pk_add_f32 v[128:129], v[108:109], v[136:137]
	v_pk_add_f32 v[108:109], v[106:107], v[170:171]
	v_mul_f32_e32 v106, v111, v111
	v_mul_f32_e32 v107, v113, v113
	v_fmac_f32_e32 v106, v110, v110
	v_fmac_f32_e32 v107, v112, v112
	v_add_f32_e32 v106, v106, v107
	v_mul_f32_e32 v107, v109, v109
	v_fmac_f32_e32 v107, v108, v108
	v_add_f32_e32 v106, v107, v106
	v_mul_f32_e32 v107, v129, v129
	v_fmac_f32_e32 v107, v128, v128
	v_add_f32_e32 v127, v107, v106
	v_cvt_pk_bf16_f32 v106, v110, v111
	v_cvt_pk_bf16_f32 v107, v112, v113
	v_lshlrev_b32_e32 v110, 16, v130
	v_and_b32_e32 v111, 0xffff0000, v130
	v_lshlrev_b32_e32 v112, 16, v131
	v_and_b32_e32 v113, 0xffff0000, v131
	v_lshlrev_b32_e32 v130, 16, v132
	v_and_b32_e32 v131, 0xffff0000, v132
	v_pk_add_f32 v[104:105], v[104:105], v[112:113]
	v_pk_add_f32 v[102:103], v[102:103], v[110:111]
	v_pk_add_f32 v[112:113], v[98:99], v[130:131]
	v_mul_f32_e32 v98, v103, v103
	v_mul_f32_e32 v99, v105, v105
	v_fmac_f32_e32 v98, v102, v102
	v_fmac_f32_e32 v99, v104, v104
	v_lshlrev_b32_e32 v132, 16, v133
	v_and_b32_e32 v133, 0xffff0000, v133
	v_add_f32_e32 v98, v98, v99
	v_mul_f32_e32 v99, v113, v113
	v_pk_add_f32 v[110:111], v[100:101], v[132:133]
	v_fmac_f32_e32 v99, v112, v112
	v_add_f32_e32 v98, v99, v98
	v_mul_f32_e32 v99, v111, v111
	v_fmac_f32_e32 v99, v110, v110
	v_add_f32_e32 v98, v99, v98
	v_add_f32_e32 v98, v127, v98
	ds_bpermute_b32 v99, v168, v98
	v_cvt_pk_bf16_f32 v108, v108, v109
	v_cvt_pk_bf16_f32 v109, v128, v129
	global_store_dwordx4 v[160:161], v[106:109], off
	v_cvt_pk_bf16_f32 v100, v102, v103
	s_waitcnt lgkmcnt(0)
	v_add_f32_e32 v98, v98, v99
	ds_bpermute_b32 v99, v126, v98
	v_cvt_pk_bf16_f32 v101, v104, v105
	v_cvt_pk_bf16_f32 v102, v112, v113
	v_cvt_pk_bf16_f32 v103, v110, v111
	global_store_dwordx4 v[160:161], v[100:103], off offset:256
	s_and_saveexec_b64 s[28:29], s[8:9]
	s_cbranch_execz .LBB0_783
	v_lshlrev_b64 v[100:101], 6, v[158:159]
	v_lshl_add_u64 v[100:101], s[18:19], 0, v[100:101]
	v_lshl_add_u64 v[100:101], s[26:27], 2, v[100:101]
	s_lshl_b32 s4, s40, 2
	v_lshl_add_u64 v[100:101], v[100:101], 0, s[4:5]
	s_waitcnt lgkmcnt(0)
	v_add_f32_e32 v98, v98, v99
	global_store_dword v[100:101], v98, off
.LBB0_783:
	s_or_b64 exec, exec, s[28:29]
	v_or_b32_e32 v106, 48, v156
	v_ashrrev_i32_e32 v107, 31, v106
	s_waitcnt lgkmcnt(0)
	v_lshlrev_b64 v[98:99], 11, v[106:107]
	v_lshl_add_u64 v[98:99], s[16:17], 0, v[98:99]
	v_lshl_add_u64 v[108:109], v[154:155], 1, v[98:99]
	s_waitcnt vmcnt(16)
	v_lshlrev_b32_e32 v110, 16, v188
	v_and_b32_e32 v111, 0xffff0000, v188
	v_lshlrev_b32_e32 v112, 16, v189
	v_and_b32_e32 v113, 0xffff0000, v189
	v_lshlrev_b32_e32 v118, 16, v190
	v_and_b32_e32 v119, 0xffff0000, v190
	v_lshlrev_b32_e32 v120, 16, v191
	v_and_b32_e32 v121, 0xffff0000, v191
	v_pk_add_f32 v[96:97], v[96:97], v[112:113]
	v_pk_add_f32 v[94:95], v[94:95], v[110:111]
	v_pk_add_f32 v[110:111], v[92:93], v[120:121]
	v_pk_add_f32 v[92:93], v[90:91], v[118:119]
	v_mul_f32_e32 v90, v95, v95
	v_mul_f32_e32 v91, v97, v97
	v_fmac_f32_e32 v90, v94, v94
	v_fmac_f32_e32 v91, v96, v96
	v_add_f32_e32 v90, v90, v91
	v_mul_f32_e32 v91, v93, v93
	v_fmac_f32_e32 v91, v92, v92
	v_add_f32_e32 v90, v91, v90
	v_mul_f32_e32 v91, v111, v111
	v_fmac_f32_e32 v91, v110, v110
	v_add_f32_e32 v118, v91, v90
	v_cvt_pk_bf16_f32 v90, v94, v95
	v_cvt_pk_bf16_f32 v91, v96, v97
	v_lshlrev_b32_e32 v94, 16, v192
	v_and_b32_e32 v95, 0xffff0000, v192
	v_lshlrev_b32_e32 v96, 16, v193
	v_and_b32_e32 v97, 0xffff0000, v193
	v_lshlrev_b32_e32 v112, 16, v194
	v_and_b32_e32 v113, 0xffff0000, v194
	v_pk_add_f32 v[88:89], v[88:89], v[96:97]
	v_pk_add_f32 v[86:87], v[86:87], v[94:95]
	v_pk_add_f32 v[96:97], v[82:83], v[112:113]
	v_mul_f32_e32 v82, v87, v87
	v_mul_f32_e32 v83, v89, v89
	v_fmac_f32_e32 v82, v86, v86
	v_fmac_f32_e32 v83, v88, v88
	v_lshlrev_b32_e32 v114, 16, v195
	v_and_b32_e32 v115, 0xffff0000, v195
	v_add_f32_e32 v82, v82, v83
	v_mul_f32_e32 v83, v97, v97
	v_pk_add_f32 v[94:95], v[84:85], v[114:115]
	v_fmac_f32_e32 v83, v96, v96
	v_add_f32_e32 v82, v83, v82
	v_mul_f32_e32 v83, v95, v95
	v_fmac_f32_e32 v83, v94, v94
	v_add_f32_e32 v82, v83, v82
	v_add_f32_e32 v82, v118, v82
	ds_bpermute_b32 v83, v168, v82
	v_cvt_pk_bf16_f32 v92, v92, v93
	v_cvt_pk_bf16_f32 v93, v110, v111
	global_store_dwordx4 v[124:125], v[90:93], off
	v_cvt_pk_bf16_f32 v84, v86, v87
	s_waitcnt lgkmcnt(0)
	v_add_f32_e32 v82, v82, v83
	ds_bpermute_b32 v83, v126, v82
	v_cvt_pk_bf16_f32 v85, v88, v89
	v_cvt_pk_bf16_f32 v86, v96, v97
	v_cvt_pk_bf16_f32 v87, v94, v95
	global_store_dwordx4 v[124:125], v[84:87], off offset:256
	s_and_saveexec_b64 s[28:29], s[8:9]
	s_cbranch_execz .LBB0_785
	v_lshlrev_b64 v[84:85], 6, v[122:123]
	v_lshl_add_u64 v[84:85], s[18:19], 0, v[84:85]
	v_lshl_add_u64 v[84:85], s[26:27], 2, v[84:85]
	s_lshl_b32 s4, s40, 2
	v_lshl_add_u64 v[84:85], v[84:85], 0, s[4:5]
	s_waitcnt lgkmcnt(0)
	v_add_f32_e32 v82, v82, v83
	global_store_dword v[84:85], v82, off
; __device__ __forceinline__ unsigned cvt_pk_bf16(float lo, float hi) { unsigned r; asm volatile("v_cvt_pk_bf16_f32 %0, %1, %2" : "=v"(r) : "v"(lo), "v"(hi)); return r; }
; __device__ __forceinline__ float bflo(unsigned w) { return __uint_as_float(w << 16); }
; __device__ __forceinline__ float bfhi(unsigned w) { return __uint_as_float(w & 0xffff0000u); }
;     __device__ __forceinline__ void operator()(const pg8::f32x4 (&acc)[2][2][4][2], const Unit& u, int wr, int wc, int fr, int fq) const {
;     ...
;         for (int k = 0; k < 8; ++k) { const int ai = k >> 2, m = k & 3; const int row = row0 + ai * HALF + m * 16; float q = 0.f; const Ld cu = nx;
;             if (k < 7) ld(nx, (size_t)(row0 + ((k + 1) >> 2) * HALF + ((k + 1) & 3) * 16) * DM_ + col0);
; #pragma unroll
;             for (int bj = 0; bj < 2; ++bj) { const size_t o = (size_t)row * DM_ + col0 + bj * HALF; f32x4 b0, b1;
;                 if (BASEF32) { b0 = cu.a[bj][0]; b1 = cu.a[bj][1]; }
;                 else { const v4u w = __builtin_bit_cast(v4u, cu.a[bj][0]); b0 = (f32x4){bflo(w.x), bfhi(w.x), bflo(w.y), bfhi(w.y)}; b1 = (f32x4){bflo(w.z), bfhi(w.z), bflo(w.w), bfhi(w.w)}; }
;                 const f32x4 r0 = b0 + acc[ai][bj][m][0], r1 = b1 + acc[ai][bj][m][1];
;                 q += (r0[0] * r0[0] + r0[1] * r0[1]) + (r0[2] * r0[2] + r0[3] * r0[3]) + (r1[0] * r1[0] + r1[1] * r1[1]) + (r1[2] * r1[2] + r1[3] * r1[3]);
;                 v4u w; w.x = cvt_pk_bf16(r0[0], r0[1]); w.y = cvt_pk_bf16(r0[2], r0[3]); w.z = cvt_pk_bf16(r1[0], r1[1]); w.w = cvt_pk_bf16(r1[2], r1[3]); *(v4u*)(out + o) = w; }
;             q += __shfl_xor(q, 16); q += __shfl_xor(q, 32); if (fq == 0) ssq[(size_t)row * 16 + u.pn * 4 + wc] = q; }
.LBB0_785:
	s_or_b64 exec, exec, s[28:29]
	v_add_u32_e32 v90, 0x80, v156
	v_ashrrev_i32_e32 v91, 31, v90
	s_waitcnt lgkmcnt(0)
	v_lshlrev_b64 v[82:83], 11, v[90:91]
	v_lshl_add_u64 v[82:83], s[16:17], 0, v[82:83]
	v_lshl_add_u64 v[92:93], v[154:155], 1, v[82:83]
	s_waitcnt vmcnt(17)
	v_lshlrev_b32_e32 v94, 16, v196
	v_and_b32_e32 v95, 0xffff0000, v196
	v_lshlrev_b32_e32 v96, 16, v197
	v_and_b32_e32 v97, 0xffff0000, v197
	v_lshlrev_b32_e32 v102, 16, v198
	v_and_b32_e32 v103, 0xffff0000, v198
	v_lshlrev_b32_e32 v104, 16, v199
	v_and_b32_e32 v105, 0xffff0000, v199
	v_pk_add_f32 v[80:81], v[80:81], v[96:97]
	v_pk_add_f32 v[78:79], v[78:79], v[94:95]
	v_pk_add_f32 v[94:95], v[76:77], v[104:105]
	v_pk_add_f32 v[76:77], v[74:75], v[102:103]
	v_mul_f32_e32 v74, v79, v79
	v_mul_f32_e32 v75, v81, v81
	v_fmac_f32_e32 v74, v78, v78
	v_fmac_f32_e32 v75, v80, v80
	v_add_f32_e32 v74, v74, v75
	v_mul_f32_e32 v75, v77, v77
	v_fmac_f32_e32 v75, v76, v76
	v_add_f32_e32 v74, v75, v74
	v_mul_f32_e32 v75, v95, v95
	v_fmac_f32_e32 v75, v94, v94
	v_add_f32_e32 v102, v75, v74
	v_cvt_pk_bf16_f32 v74, v78, v79
	v_cvt_pk_bf16_f32 v75, v80, v81
	v_lshlrev_b32_e32 v78, 16, v200
	v_and_b32_e32 v79, 0xffff0000, v200
	v_lshlrev_b32_e32 v80, 16, v201
	v_and_b32_e32 v81, 0xffff0000, v201
	v_lshlrev_b32_e32 v96, 16, v202
	v_and_b32_e32 v97, 0xffff0000, v202
	v_pk_add_f32 v[72:73], v[72:73], v[80:81]
	v_pk_add_f32 v[70:71], v[70:71], v[78:79]
	v_pk_add_f32 v[80:81], v[66:67], v[96:97]
	v_mul_f32_e32 v66, v71, v71
	v_mul_f32_e32 v67, v73, v73
	v_fmac_f32_e32 v66, v70, v70
	v_fmac_f32_e32 v67, v72, v72
	v_lshlrev_b32_e32 v98, 16, v203
	v_and_b32_e32 v99, 0xffff0000, v203
	v_add_f32_e32 v66, v66, v67
	v_mul_f32_e32 v67, v81, v81
	v_pk_add_f32 v[78:79], v[68:69], v[98:99]
	v_fmac_f32_e32 v67, v80, v80
	v_add_f32_e32 v66, v67, v66
	v_mul_f32_e32 v67, v79, v79
	v_fmac_f32_e32 v67, v78, v78
	v_add_f32_e32 v66, v67, v66
	v_add_f32_e32 v66, v102, v66
	ds_bpermute_b32 v67, v168, v66
	v_cvt_pk_bf16_f32 v76, v76, v77
	v_cvt_pk_bf16_f32 v77, v94, v95
	global_store_dwordx4 v[108:109], v[74:77], off
	v_cvt_pk_bf16_f32 v68, v70, v71
	s_waitcnt lgkmcnt(0)
	v_add_f32_e32 v66, v66, v67
	ds_bpermute_b32 v67, v126, v66
	v_cvt_pk_bf16_f32 v69, v72, v73
	v_cvt_pk_bf16_f32 v70, v80, v81
	v_cvt_pk_bf16_f32 v71, v78, v79
	global_store_dwordx4 v[108:109], v[68:71], off offset:256
	s_and_saveexec_b64 s[28:29], s[8:9]
	s_cbranch_execz .LBB0_787
	v_lshlrev_b64 v[68:69], 6, v[106:107]
	v_lshl_add_u64 v[68:69], s[18:19], 0, v[68:69]
	v_lshl_add_u64 v[68:69], s[26:27], 2, v[68:69]
	s_lshl_b32 s4, s40, 2
	v_lshl_add_u64 v[68:69], v[68:69], 0, s[4:5]
	s_waitcnt lgkmcnt(0)
	v_add_f32_e32 v66, v66, v67
	global_store_dword v[68:69], v66, off
.LBB0_787:
	s_or_b64 exec, exec, s[28:29]
	v_or_b32_e32 v74, 16, v90
	v_ashrrev_i32_e32 v75, 31, v74
	s_waitcnt lgkmcnt(0)
	v_lshlrev_b64 v[66:67], 11, v[74:75]
	v_lshl_add_u64 v[66:67], s[16:17], 0, v[66:67]
	v_lshl_add_u64 v[76:77], v[154:155], 1, v[66:67]
	s_waitcnt vmcnt(18)
	v_lshlrev_b32_e32 v78, 16, v204
	v_and_b32_e32 v79, 0xffff0000, v204
	v_lshlrev_b32_e32 v80, 16, v205
	v_and_b32_e32 v81, 0xffff0000, v205
	v_lshlrev_b32_e32 v86, 16, v206
	v_and_b32_e32 v87, 0xffff0000, v206
	v_lshlrev_b32_e32 v88, 16, v207
	v_and_b32_e32 v89, 0xffff0000, v207
	v_pk_add_f32 v[64:65], v[64:65], v[80:81]
	v_pk_add_f32 v[62:63], v[62:63], v[78:79]
	v_pk_add_f32 v[78:79], v[60:61], v[88:89]
	v_pk_add_f32 v[60:61], v[58:59], v[86:87]
	v_mul_f32_e32 v58, v63, v63
	v_mul_f32_e32 v59, v65, v65
	v_fmac_f32_e32 v58, v62, v62
	v_fmac_f32_e32 v59, v64, v64
	v_add_f32_e32 v58, v58, v59
	v_mul_f32_e32 v59, v61, v61
	v_fmac_f32_e32 v59, v60, v60
	v_add_f32_e32 v58, v59, v58
	v_mul_f32_e32 v59, v79, v79
	v_fmac_f32_e32 v59, v78, v78
	v_add_f32_e32 v86, v59, v58
	v_cvt_pk_bf16_f32 v58, v62, v63
	v_cvt_pk_bf16_f32 v59, v64, v65
	v_lshlrev_b32_e32 v62, 16, v208
	v_and_b32_e32 v63, 0xffff0000, v208
	v_lshlrev_b32_e32 v64, 16, v209
	v_and_b32_e32 v65, 0xffff0000, v209
	v_lshlrev_b32_e32 v80, 16, v210
	v_and_b32_e32 v81, 0xffff0000, v210
	v_pk_add_f32 v[56:57], v[56:57], v[64:65]
	v_pk_add_f32 v[54:55], v[54:55], v[62:63]
	v_pk_add_f32 v[64:65], v[50:51], v[80:81]
	v_mul_f32_e32 v50, v55, v55
	v_mul_f32_e32 v51, v57, v57
	v_fmac_f32_e32 v50, v54, v54
	v_fmac_f32_e32 v51, v56, v56
	v_lshlrev_b32_e32 v82, 16, v211
	v_and_b32_e32 v83, 0xffff0000, v211
	v_add_f32_e32 v50, v50, v51
	v_mul_f32_e32 v51, v65, v65
	v_pk_add_f32 v[62:63], v[52:53], v[82:83]
	v_fmac_f32_e32 v51, v64, v64
	v_add_f32_e32 v50, v51, v50
	v_mul_f32_e32 v51, v63, v63
	v_fmac_f32_e32 v51, v62, v62
	v_add_f32_e32 v50, v51, v50
	v_add_f32_e32 v50, v86, v50
	ds_bpermute_b32 v51, v168, v50
	v_cvt_pk_bf16_f32 v60, v60, v61
	v_cvt_pk_bf16_f32 v61, v78, v79
	global_store_dwordx4 v[92:93], v[58:61], off
	v_cvt_pk_bf16_f32 v52, v54, v55
	s_waitcnt lgkmcnt(0)
	v_add_f32_e32 v50, v50, v51
	ds_bpermute_b32 v51, v126, v50
	v_cvt_pk_bf16_f32 v53, v56, v57
	v_cvt_pk_bf16_f32 v54, v64, v65
	v_cvt_pk_bf16_f32 v55, v62, v63
	global_store_dwordx4 v[92:93], v[52:55], off offset:256
	s_and_saveexec_b64 s[28:29], s[8:9]
	s_cbranch_execz .LBB0_789
	v_lshlrev_b64 v[52:53], 6, v[90:91]
	v_lshl_add_u64 v[52:53], s[18:19], 0, v[52:53]
	v_lshl_add_u64 v[52:53], s[26:27], 2, v[52:53]
	s_lshl_b32 s4, s40, 2
	v_lshl_add_u64 v[52:53], v[52:53], 0, s[4:5]
	s_waitcnt lgkmcnt(0)
	v_add_f32_e32 v50, v50, v51
	global_store_dword v[52:53], v50, off
; __device__ __forceinline__ unsigned cvt_pk_bf16(float lo, float hi) { unsigned r; asm volatile("v_cvt_pk_bf16_f32 %0, %1, %2" : "=v"(r) : "v"(lo), "v"(hi)); return r; }
; __device__ __forceinline__ float bflo(unsigned w) { return __uint_as_float(w << 16); }
; __device__ __forceinline__ float bfhi(unsigned w) { return __uint_as_float(w & 0xffff0000u); }
;     __device__ __forceinline__ void operator()(const pg8::f32x4 (&acc)[2][2][4][2], const Unit& u, int wr, int wc, int fr, int fq) const {
;     ...
;         for (int k = 0; k < 8; ++k) { const int ai = k >> 2, m = k & 3; const int row = row0 + ai * HALF + m * 16; float q = 0.f; const Ld cu = nx;
;             if (k < 7) ld(nx, (size_t)(row0 + ((k + 1) >> 2) * HALF + ((k + 1) & 3) * 16) * DM_ + col0);
; #pragma unroll
;             for (int bj = 0; bj < 2; ++bj) { const size_t o = (size_t)row * DM_ + col0 + bj * HALF; f32x4 b0, b1;
;                 if (BASEF32) { b0 = cu.a[bj][0]; b1 = cu.a[bj][1]; }
;                 else { const v4u w = __builtin_bit_cast(v4u, cu.a[bj][0]); b0 = (f32x4){bflo(w.x), bfhi(w.x), bflo(w.y), bfhi(w.y)}; b1 = (f32x4){bflo(w.z), bfhi(w.z), bflo(w.w), bfhi(w.w)}; }
;                 const f32x4 r0 = b0 + acc[ai][bj][m][0], r1 = b1 + acc[ai][bj][m][1];
;                 q += (r0[0] * r0[0] + r0[1] * r0[1]) + (r0[2] * r0[2] + r0[3] * r0[3]) + (r1[0] * r1[0] + r1[1] * r1[1]) + (r1[2] * r1[2] + r1[3] * r1[3]);
;                 v4u w; w.x = cvt_pk_bf16(r0[0], r0[1]); w.y = cvt_pk_bf16(r0[2], r0[3]); w.z = cvt_pk_bf16(r1[0], r1[1]); w.w = cvt_pk_bf16(r1[2], r1[3]); *(v4u*)(out + o) = w; }
;             q += __shfl_xor(q, 16); q += __shfl_xor(q, 32); if (fq == 0) ssq[(size_t)row * 16 + u.pn * 4 + wc] = q; }
.LBB0_789:
	s_or_b64 exec, exec, s[28:29]
	v_or_b32_e32 v58, 32, v90
	v_ashrrev_i32_e32 v59, 31, v58
	s_waitcnt lgkmcnt(0)
	v_lshlrev_b64 v[50:51], 11, v[58:59]
	v_lshl_add_u64 v[50:51], s[16:17], 0, v[50:51]
	v_lshl_add_u64 v[60:61], v[154:155], 1, v[50:51]
	s_waitcnt vmcnt(19)
	v_lshlrev_b32_e32 v62, 16, v212
	v_and_b32_e32 v63, 0xffff0000, v212
	v_lshlrev_b32_e32 v64, 16, v213
	v_and_b32_e32 v65, 0xffff0000, v213
	v_lshlrev_b32_e32 v70, 16, v214
	v_and_b32_e32 v71, 0xffff0000, v214
	v_lshlrev_b32_e32 v72, 16, v215
	v_and_b32_e32 v73, 0xffff0000, v215
	v_pk_add_f32 v[48:49], v[48:49], v[64:65]
	v_pk_add_f32 v[46:47], v[46:47], v[62:63]
	v_pk_add_f32 v[62:63], v[44:45], v[72:73]
	v_pk_add_f32 v[44:45], v[42:43], v[70:71]
	v_mul_f32_e32 v42, v47, v47
	v_mul_f32_e32 v43, v49, v49
	v_fmac_f32_e32 v42, v46, v46
	v_fmac_f32_e32 v43, v48, v48
	v_add_f32_e32 v42, v42, v43
	v_mul_f32_e32 v43, v45, v45
	v_fmac_f32_e32 v43, v44, v44
	v_add_f32_e32 v42, v43, v42
	v_mul_f32_e32 v43, v63, v63
	v_fmac_f32_e32 v43, v62, v62
	v_add_f32_e32 v70, v43, v42
	v_cvt_pk_bf16_f32 v42, v46, v47
	v_cvt_pk_bf16_f32 v43, v48, v49
	v_lshlrev_b32_e32 v46, 16, v230
	v_and_b32_e32 v47, 0xffff0000, v230
	v_lshlrev_b32_e32 v48, 16, v231
	v_and_b32_e32 v49, 0xffff0000, v231
	v_lshlrev_b32_e32 v64, 16, v232
	v_and_b32_e32 v65, 0xffff0000, v232
	v_pk_add_f32 v[40:41], v[40:41], v[48:49]
	v_pk_add_f32 v[38:39], v[38:39], v[46:47]
	v_pk_add_f32 v[48:49], v[34:35], v[64:65]
	v_mul_f32_e32 v34, v39, v39
	v_mul_f32_e32 v35, v41, v41
	v_fmac_f32_e32 v34, v38, v38
	v_fmac_f32_e32 v35, v40, v40
	v_lshlrev_b32_e32 v66, 16, v233
	v_and_b32_e32 v67, 0xffff0000, v233
	v_add_f32_e32 v34, v34, v35
	v_mul_f32_e32 v35, v49, v49
	v_pk_add_f32 v[46:47], v[36:37], v[66:67]
	v_fmac_f32_e32 v35, v48, v48
	v_add_f32_e32 v34, v35, v34
	v_mul_f32_e32 v35, v47, v47
	v_fmac_f32_e32 v35, v46, v46
	v_add_f32_e32 v34, v35, v34
	v_add_f32_e32 v34, v70, v34
	ds_bpermute_b32 v35, v168, v34
	v_cvt_pk_bf16_f32 v44, v44, v45
	v_cvt_pk_bf16_f32 v45, v62, v63
	global_store_dwordx4 v[76:77], v[42:45], off
	v_cvt_pk_bf16_f32 v36, v38, v39
	s_waitcnt lgkmcnt(0)
	v_add_f32_e32 v34, v34, v35
	ds_bpermute_b32 v35, v126, v34
	v_cvt_pk_bf16_f32 v37, v40, v41
	v_cvt_pk_bf16_f32 v38, v48, v49
	v_cvt_pk_bf16_f32 v39, v46, v47
	global_store_dwordx4 v[76:77], v[36:39], off offset:256
	s_and_saveexec_b64 s[28:29], s[8:9]
	s_cbranch_execz .LBB0_791
	v_lshlrev_b64 v[36:37], 6, v[74:75]
	v_lshl_add_u64 v[36:37], s[18:19], 0, v[36:37]
	v_lshl_add_u64 v[36:37], s[26:27], 2, v[36:37]
	s_lshl_b32 s4, s40, 2
	v_lshl_add_u64 v[36:37], v[36:37], 0, s[4:5]
	s_waitcnt lgkmcnt(0)
	v_add_f32_e32 v34, v34, v35
	global_store_dword v[36:37], v34, off
; __device__ __forceinline__ unsigned cvt_pk_bf16(float lo, float hi) { unsigned r; asm volatile("v_cvt_pk_bf16_f32 %0, %1, %2" : "=v"(r) : "v"(lo), "v"(hi)); return r; }
; __device__ __forceinline__ float bflo(unsigned w) { return __uint_as_float(w << 16); }
; __device__ __forceinline__ float bfhi(unsigned w) { return __uint_as_float(w & 0xffff0000u); }
;     __device__ __forceinline__ void operator()(const pg8::f32x4 (&acc)[2][2][4][2], const Unit& u, int wr, int wc, int fr, int fq) const {
;     ...
;         for (int k = 0; k < 8; ++k) { const int ai = k >> 2, m = k & 3; const int row = row0 + ai * HALF + m * 16; float q = 0.f; const Ld cu = nx;
;             if (k < 7) ld(nx, (size_t)(row0 + ((k + 1) >> 2) * HALF + ((k + 1) & 3) * 16) * DM_ + col0);
; #pragma unroll
;             for (int bj = 0; bj < 2; ++bj) { const size_t o = (size_t)row * DM_ + col0 + bj * HALF; f32x4 b0, b1;
;                 if (BASEF32) { b0 = cu.a[bj][0]; b1 = cu.a[bj][1]; }
;                 else { const v4u w = __builtin_bit_cast(v4u, cu.a[bj][0]); b0 = (f32x4){bflo(w.x), bfhi(w.x), bflo(w.y), bfhi(w.y)}; b1 = (f32x4){bflo(w.z), bfhi(w.z), bflo(w.w), bfhi(w.w)}; }
;                 const f32x4 r0 = b0 + acc[ai][bj][m][0], r1 = b1 + acc[ai][bj][m][1];
;                 q += (r0[0] * r0[0] + r0[1] * r0[1]) + (r0[2] * r0[2] + r0[3] * r0[3]) + (r1[0] * r1[0] + r1[1] * r1[1]) + (r1[2] * r1[2] + r1[3] * r1[3]);
;                 v4u w; w.x = cvt_pk_bf16(r0[0], r0[1]); w.y = cvt_pk_bf16(r0[2], r0[3]); w.z = cvt_pk_bf16(r1[0], r1[1]); w.w = cvt_pk_bf16(r1[2], r1[3]); *(v4u*)(out + o) = w; }
;             q += __shfl_xor(q, 16); q += __shfl_xor(q, 32); if (fq == 0) ssq[(size_t)row * 16 + u.pn * 4 + wc] = q; }
.LBB0_791:
	s_or_b64 exec, exec, s[28:29]
	v_or_b32_e32 v42, 48, v90
	v_ashrrev_i32_e32 v43, 31, v42
	s_waitcnt lgkmcnt(0)
	v_lshlrev_b64 v[34:35], 11, v[42:43]
	v_lshl_add_u64 v[34:35], s[16:17], 0, v[34:35]
	v_lshl_add_u64 v[44:45], v[154:155], 1, v[34:35]
	s_waitcnt vmcnt(20)
	v_lshlrev_b32_e32 v46, 16, v234
	v_and_b32_e32 v47, 0xffff0000, v234
	v_lshlrev_b32_e32 v48, 16, v235
	v_and_b32_e32 v49, 0xffff0000, v235
	v_lshlrev_b32_e32 v54, 16, v236
	v_and_b32_e32 v55, 0xffff0000, v236
	v_lshlrev_b32_e32 v56, 16, v237
	v_and_b32_e32 v57, 0xffff0000, v237
	v_pk_add_f32 v[32:33], v[32:33], v[48:49]
	v_pk_add_f32 v[30:31], v[30:31], v[46:47]
	v_pk_add_f32 v[46:47], v[28:29], v[56:57]
	v_pk_add_f32 v[28:29], v[26:27], v[54:55]
	v_mul_f32_e32 v26, v31, v31
	v_mul_f32_e32 v27, v33, v33
	v_fmac_f32_e32 v26, v30, v30
	v_fmac_f32_e32 v27, v32, v32
	v_add_f32_e32 v26, v26, v27
	v_mul_f32_e32 v27, v29, v29
	v_fmac_f32_e32 v27, v28, v28
	v_add_f32_e32 v26, v27, v26
	v_mul_f32_e32 v27, v47, v47
	v_fmac_f32_e32 v27, v46, v46
	v_add_f32_e32 v54, v27, v26
	v_cvt_pk_bf16_f32 v26, v30, v31
	v_cvt_pk_bf16_f32 v27, v32, v33
	v_lshlrev_b32_e32 v30, 16, v238
	v_and_b32_e32 v31, 0xffff0000, v238
	v_lshlrev_b32_e32 v32, 16, v239
	v_and_b32_e32 v33, 0xffff0000, v239
	v_lshlrev_b32_e32 v48, 16, v240
	v_and_b32_e32 v49, 0xffff0000, v240
	v_pk_add_f32 v[24:25], v[24:25], v[32:33]
	v_pk_add_f32 v[22:23], v[22:23], v[30:31]
	v_pk_add_f32 v[32:33], v[18:19], v[48:49]
	v_mul_f32_e32 v18, v23, v23
	v_mul_f32_e32 v19, v25, v25
	v_fmac_f32_e32 v18, v22, v22
	v_fmac_f32_e32 v19, v24, v24
	v_lshlrev_b32_e32 v50, 16, v241
	v_and_b32_e32 v51, 0xffff0000, v241
	v_add_f32_e32 v18, v18, v19
	v_mul_f32_e32 v19, v33, v33
	v_pk_add_f32 v[30:31], v[20:21], v[50:51]
	v_fmac_f32_e32 v19, v32, v32
	v_add_f32_e32 v18, v19, v18
	v_mul_f32_e32 v19, v31, v31
	v_fmac_f32_e32 v19, v30, v30
	v_add_f32_e32 v18, v19, v18
	v_add_f32_e32 v18, v54, v18
	ds_bpermute_b32 v19, v168, v18
	v_cvt_pk_bf16_f32 v28, v28, v29
	v_cvt_pk_bf16_f32 v29, v46, v47
	global_store_dwordx4 v[60:61], v[26:29], off
	v_cvt_pk_bf16_f32 v20, v22, v23
	s_waitcnt lgkmcnt(0)
	v_add_f32_e32 v18, v18, v19
	ds_bpermute_b32 v19, v126, v18
	v_cvt_pk_bf16_f32 v21, v24, v25
	v_cvt_pk_bf16_f32 v22, v32, v33
	v_cvt_pk_bf16_f32 v23, v30, v31
	global_store_dwordx4 v[60:61], v[20:23], off offset:256
	s_and_saveexec_b64 s[28:29], s[8:9]
	s_cbranch_execz .LBB0_793
	v_lshlrev_b64 v[20:21], 6, v[58:59]
	v_lshl_add_u64 v[20:21], s[18:19], 0, v[20:21]
	v_lshl_add_u64 v[20:21], s[26:27], 2, v[20:21]
	s_lshl_b32 s4, s40, 2
	v_lshl_add_u64 v[20:21], v[20:21], 0, s[4:5]
	s_waitcnt lgkmcnt(0)
	v_add_f32_e32 v18, v18, v19
	global_store_dword v[20:21], v18, off
.LBB0_793:
	s_or_b64 exec, exec, s[28:29]
	s_waitcnt vmcnt(21)
	v_lshlrev_b32_e32 v18, 16, v242
	s_waitcnt lgkmcnt(0)
	v_and_b32_e32 v19, 0xffff0000, v242
	v_lshlrev_b32_e32 v20, 16, v243
	v_and_b32_e32 v21, 0xffff0000, v243
	v_lshlrev_b32_e32 v22, 16, v244
	v_and_b32_e32 v23, 0xffff0000, v244
	v_lshlrev_b32_e32 v24, 16, v245
	v_and_b32_e32 v25, 0xffff0000, v245
	v_pk_add_f32 v[16:17], v[16:17], v[20:21]
	v_pk_add_f32 v[14:15], v[14:15], v[18:19]
	v_pk_add_f32 v[18:19], v[12:13], v[24:25]
	v_pk_add_f32 v[12:13], v[10:11], v[22:23]
	v_mul_f32_e32 v10, v15, v15
	v_mul_f32_e32 v11, v17, v17
	v_fmac_f32_e32 v10, v14, v14
	v_fmac_f32_e32 v11, v16, v16
	v_add_f32_e32 v10, v10, v11
	v_mul_f32_e32 v11, v13, v13
	v_fmac_f32_e32 v11, v12, v12
	v_add_f32_e32 v10, v11, v10
	v_mul_f32_e32 v11, v19, v19
	v_fmac_f32_e32 v11, v18, v18
	v_add_f32_e32 v24, v11, v10
	v_cvt_pk_bf16_f32 v10, v14, v15
	v_cvt_pk_bf16_f32 v11, v16, v17
	v_lshlrev_b32_e32 v14, 16, v246
	v_and_b32_e32 v15, 0xffff0000, v246
	v_lshlrev_b32_e32 v16, 16, v247
	v_and_b32_e32 v17, 0xffff0000, v247
	v_lshlrev_b32_e32 v20, 16, v248
	v_and_b32_e32 v21, 0xffff0000, v248
	v_pk_add_f32 v[8:9], v[8:9], v[16:17]
	v_pk_add_f32 v[6:7], v[6:7], v[14:15]
	v_pk_add_f32 v[16:17], v[2:3], v[20:21]
	v_mul_f32_e32 v2, v7, v7
	v_mul_f32_e32 v3, v9, v9
	v_fmac_f32_e32 v2, v6, v6
	v_fmac_f32_e32 v3, v8, v8
	v_lshlrev_b32_e32 v22, 16, v249
	v_and_b32_e32 v23, 0xffff0000, v249
	v_add_f32_e32 v2, v2, v3
	v_mul_f32_e32 v3, v17, v17
	v_pk_add_f32 v[14:15], v[4:5], v[22:23]
	v_fmac_f32_e32 v3, v16, v16
	v_add_f32_e32 v2, v3, v2
	v_mul_f32_e32 v3, v15, v15
	v_fmac_f32_e32 v3, v14, v14
	v_add_f32_e32 v2, v3, v2
	v_add_f32_e32 v2, v24, v2
	ds_bpermute_b32 v3, v168, v2
	v_cvt_pk_bf16_f32 v12, v12, v13
	v_cvt_pk_bf16_f32 v13, v18, v19
	global_store_dwordx4 v[44:45], v[10:13], off
	v_cvt_pk_bf16_f32 v4, v6, v7
	s_waitcnt lgkmcnt(0)
	v_add_f32_e32 v2, v2, v3
	ds_bpermute_b32 v3, v126, v2
	v_cvt_pk_bf16_f32 v5, v8, v9
	v_cvt_pk_bf16_f32 v6, v16, v17
	v_cvt_pk_bf16_f32 v7, v14, v15
	global_store_dwordx4 v[44:45], v[4:7], off offset:256
	s_and_saveexec_b64 s[28:29], s[8:9]
	s_cbranch_execz .LBB0_795
	v_lshlrev_b64 v[4:5], 6, v[42:43]
	v_lshl_add_u64 v[4:5], s[18:19], 0, v[4:5]
	v_lshl_add_u64 v[4:5], s[26:27], 2, v[4:5]
	s_lshl_b32 s4, s40, 2
	v_lshl_add_u64 v[4:5], v[4:5], 0, s[4:5]
	s_waitcnt lgkmcnt(0)
	v_add_f32_e32 v2, v2, v3
	global_store_dword v[4:5], v2, off
